# LN1 and LN2 grid barriers replaced by signal counters; consumer GEMMs wait lazily before sample-row tiles
# speedup vs baseline: 1.0062x; 1.0062x over previous
.LBB0_227:
	s_cmp_lt_i32 s34, 64
	s_cbranch_scc1 lnw_skip_2
	v_readlane_b32 vcc_lo, v255, 13
	s_cmp_eq_u32 vcc_lo, 0
	s_cbranch_scc1 lnw_skip_2
	s_load_dwordx2 s[100:101], s[0:1], 0xc0
	s_lshl_b32 vcc_lo, vcc_lo, 5
	s_addk_i32 vcc_lo, 0x1300
	s_waitcnt lgkmcnt(0)
	s_add_u32 s100, s100, vcc_lo
	s_addc_u32 s101, s101, 0
	s_mov_b32 vcc_hi, 0
lnw_loop_2:
	global_load_dword v0, v17, s[100:101] sc1
	s_waitcnt vmcnt(0)
	v_readfirstlane_b32 vcc_lo, v0
	s_cmp_ge_u32 vcc_lo, s56
	s_cbranch_scc1 lnw_skip_2
	s_sleep 4
	s_add_i32 vcc_hi, vcc_hi, 1
	s_cmp_lt_u32 vcc_hi, 0x20000
	s_cbranch_scc1 lnw_loop_2
lnw_skip_2:
	s_ashr_i32 s35, s34, 31
	s_lshl_b64 s[26:27], s[34:35], 19
	s_add_u32 s36, s43, s26
	s_addc_u32 s37, s80, s27
	s_and_b64 s[26:27], s[4:5], exec
	s_cselect_b32 s7, s37, s11
	s_cselect_b32 s9, s36, s10
	s_ashr_i32 s31, s30, 31
	s_lshl_b64 s[26:27], s[30:31], 19
	v_readlane_b32 s31, v255, 14
	s_add_u32 s38, s31, s26
	v_readlane_b32 s26, v255, 16
	s_addc_u32 s39, s26, s27
	s_and_b64 s[26:27], s[4:5], exec
	s_cselect_b32 s26, s39, s13
	s_cselect_b32 s27, s38, s12
	s_add_u32 s10, s10, 0x40080
	s_addc_u32 s11, s11, 0
	s_add_u32 s31, s12, 0x100
	v_mov_b32_e32 v0, 0
	s_addc_u32 s35, s13, 0
	s_mov_b32 s42, -2
	v_mov_b32_e32 v1, v0
	v_mov_b32_e32 v2, v0
	v_mov_b32_e32 v3, v0
	v_mov_b32_e32 v4, v0
	v_mov_b32_e32 v5, v0
	v_mov_b32_e32 v6, v0
	v_mov_b32_e32 v7, v0
	v_mov_b32_e32 v18, v0
	v_mov_b32_e32 v19, v0
	v_mov_b32_e32 v20, v0
	v_mov_b32_e32 v21, v0
	v_mov_b32_e32 v22, v0
	v_mov_b32_e32 v23, v0
	v_mov_b32_e32 v24, v0
	v_mov_b32_e32 v25, v0
	v_mov_b32_e32 v34, v0
	v_mov_b32_e32 v35, v0
	v_mov_b32_e32 v36, v0
	v_mov_b32_e32 v37, v0
	v_mov_b32_e32 v38, v0
	v_mov_b32_e32 v39, v0
	v_mov_b32_e32 v40, v0
	v_mov_b32_e32 v41, v0
	v_mov_b32_e32 v50, v0
	v_mov_b32_e32 v51, v0
	v_mov_b32_e32 v52, v0
	v_mov_b32_e32 v53, v0
	v_mov_b32_e32 v54, v0
	v_mov_b32_e32 v55, v0
	v_mov_b32_e32 v56, v0
	v_mov_b32_e32 v57, v0
	v_mov_b32_e32 v8, v0
	v_mov_b32_e32 v9, v0
	v_mov_b32_e32 v10, v0
	v_mov_b32_e32 v11, v0
	v_mov_b32_e32 v12, v0
	v_mov_b32_e32 v13, v0
	v_mov_b32_e32 v14, v0
	v_mov_b32_e32 v15, v0
	v_mov_b32_e32 v26, v0
	v_mov_b32_e32 v27, v0
	v_mov_b32_e32 v28, v0
	v_mov_b32_e32 v29, v0
	v_mov_b32_e32 v30, v0
	v_mov_b32_e32 v31, v0
	v_mov_b32_e32 v32, v0
	v_mov_b32_e32 v33, v0
	v_mov_b32_e32 v42, v0
	v_mov_b32_e32 v43, v0
	v_mov_b32_e32 v44, v0
	v_mov_b32_e32 v45, v0
	v_mov_b32_e32 v46, v0
	v_mov_b32_e32 v47, v0
	v_mov_b32_e32 v48, v0
	v_mov_b32_e32 v49, v0
	v_mov_b32_e32 v58, v0
	v_mov_b32_e32 v59, v0
	v_mov_b32_e32 v60, v0
	v_mov_b32_e32 v61, v0
	v_mov_b32_e32 v62, v0
	v_mov_b32_e32 v63, v0
	v_mov_b32_e32 v64, v0
	v_mov_b32_e32 v65, v0
	v_mov_b32_e32 v66, v0
	v_mov_b32_e32 v67, v0
	v_mov_b32_e32 v68, v0
	v_mov_b32_e32 v69, v0
	v_mov_b32_e32 v70, v0
	v_mov_b32_e32 v71, v0
	v_mov_b32_e32 v72, v0
	v_mov_b32_e32 v73, v0
	v_mov_b32_e32 v82, v0
	v_mov_b32_e32 v83, v0
	v_mov_b32_e32 v84, v0
	v_mov_b32_e32 v85, v0
	v_mov_b32_e32 v86, v0
	v_mov_b32_e32 v87, v0
	v_mov_b32_e32 v88, v0
	v_mov_b32_e32 v89, v0
	v_mov_b32_e32 v98, v0
	v_mov_b32_e32 v99, v0
	v_mov_b32_e32 v100, v0
	v_mov_b32_e32 v101, v0
	v_mov_b32_e32 v102, v0
	v_mov_b32_e32 v103, v0
	v_mov_b32_e32 v104, v0
	v_mov_b32_e32 v105, v0
	v_mov_b32_e32 v114, v0
	v_mov_b32_e32 v115, v0
	v_mov_b32_e32 v116, v0
	v_mov_b32_e32 v117, v0
	v_mov_b32_e32 v118, v0
	v_mov_b32_e32 v119, v0
	v_mov_b32_e32 v120, v0
	v_mov_b32_e32 v121, v0
	v_mov_b32_e32 v74, v0
	v_mov_b32_e32 v75, v0
	v_mov_b32_e32 v76, v0
	v_mov_b32_e32 v77, v0
	v_mov_b32_e32 v78, v0
	v_mov_b32_e32 v79, v0
	v_mov_b32_e32 v80, v0
	v_mov_b32_e32 v81, v0
	v_mov_b32_e32 v90, v0
	v_mov_b32_e32 v91, v0
	v_mov_b32_e32 v92, v0
	v_mov_b32_e32 v93, v0
	v_mov_b32_e32 v94, v0
	v_mov_b32_e32 v95, v0
	v_mov_b32_e32 v96, v0
	v_mov_b32_e32 v97, v0
	v_mov_b32_e32 v106, v0
	v_mov_b32_e32 v107, v0
	v_mov_b32_e32 v108, v0
	v_mov_b32_e32 v109, v0
	v_mov_b32_e32 v110, v0
	v_mov_b32_e32 v111, v0
	v_mov_b32_e32 v112, v0
	v_mov_b32_e32 v113, v0
	v_mov_b32_e32 v122, v0
	v_mov_b32_e32 v123, v0
	v_mov_b32_e32 v124, v0
	v_mov_b32_e32 v125, v0
	v_mov_b32_e32 v126, v0
	v_mov_b32_e32 v127, v0
	v_mov_b32_e32 v128, v0
	v_mov_b32_e32 v129, v0

.LBB0_2325:
	s_load_dword s4, s[0:1], 0xd0
	s_waitcnt lgkmcnt(0)
	s_cmp_lg_u32 s4, 0
	s_cbranch_scc0 .LBB0_2382
	s_or_b32 s4, s60, 7
	s_load_dword s5, s[0:1], 0xcc
	s_waitcnt lgkmcnt(0)
	s_cmp_ge_i32 s4, s5
	s_cbranch_scc1 .LBB0_2382
	s_load_dwordx2 s[6:7], s[0:1], 0xc0
	s_waitcnt lgkmcnt(0)
	s_getreg_b32 s8, hwreg(HW_REG_XCC_ID, 0, 4)
	s_waitcnt vmcnt(0)
	s_cmp_lg_u32 s33, 0
	s_waitcnt vmcnt(0) lgkmcnt(0)
	s_barrier
	s_cbranch_scc1 .LBB0_2381
	v_cmp_eq_u32_e32 vcc, 0, v245
	s_and_saveexec_b64 s[4:5], vcc
	s_cbranch_execz .LBB0_2380
	buffer_wbl2 sc1
	s_waitcnt vmcnt(0)
	v_readlane_b32 s8, v255, 13
	s_lshl_b32 s8, s8, 5
	s_add_u32 s8, s6, s8
	s_addc_u32 s9, s7, 0
	s_add_u32 s8, s8, 0x1000
	s_addc_u32 s9, s9, 0
	global_atomic_add v17, v237, s[8:9]

.LBB0_2400:
	s_cmp_lt_i32 s16, 64
	s_cbranch_scc1 lnw_skip_1
	s_load_dwordx2 s[100:101], s[0:1], 0xc0
	v_readlane_b32 vcc_lo, v255, 13
	s_lshl_b32 vcc_lo, vcc_lo, 5
	s_addk_i32 vcc_lo, 0x1000
	s_waitcnt lgkmcnt(0)
	s_add_u32 s100, s100, vcc_lo
	s_addc_u32 s101, s101, 0
	s_mov_b32 vcc_hi, 0
lnw_loop_1:
	global_load_dword v0, v17, s[100:101] sc1
	s_waitcnt vmcnt(0)
	v_readfirstlane_b32 vcc_lo, v0
	s_cmp_ge_u32 vcc_lo, s34
	s_cbranch_scc1 lnw_done_1
	s_sleep 4
	s_add_i32 vcc_hi, vcc_hi, 1
	s_cmp_lt_u32 vcc_hi, 0x20000
	s_cbranch_scc1 lnw_loop_1
lnw_done_1:
lnw_skip_1:
	s_ashr_i32 s17, s16, 31
	s_lshl_b64 s[18:19], s[16:17], 19
	s_add_u32 s18, s38, s18
	s_addc_u32 s19, s39, s19
	s_and_b64 s[20:21], s[4:5], exec
	s_cselect_b32 s17, s19, s25
	s_cselect_b32 s63, s18, s24
	s_ashr_i32 s15, s14, 31
	s_lshl_b64 s[20:21], s[14:15], 19
	s_add_u32 s20, s40, s20
	s_addc_u32 s21, s41, s21
	s_and_b64 s[28:29], s[4:5], exec
	s_cselect_b32 s15, s21, s27
	s_cselect_b32 s64, s20, s26
	s_add_u32 s24, s24, 0x40080
	s_addc_u32 s25, s25, 0
	s_add_u32 s65, s26, 0x100
	v_mov_b32_e32 v0, 0
	s_addc_u32 s68, s27, 0
	s_mov_b32 s69, -2
	v_mov_b32_e32 v1, v0
	v_mov_b32_e32 v2, v0
	v_mov_b32_e32 v3, v0
	v_mov_b32_e32 v8, v0
	v_mov_b32_e32 v9, v0
	v_mov_b32_e32 v10, v0
	v_mov_b32_e32 v11, v0
	v_mov_b32_e32 v18, v0
	v_mov_b32_e32 v19, v0
	v_mov_b32_e32 v20, v0
	v_mov_b32_e32 v21, v0
	v_mov_b32_e32 v26, v0
	v_mov_b32_e32 v27, v0
	v_mov_b32_e32 v28, v0
	v_mov_b32_e32 v29, v0
	v_mov_b32_e32 v34, v0
	v_mov_b32_e32 v35, v0
	v_mov_b32_e32 v36, v0
	v_mov_b32_e32 v37, v0
	v_mov_b32_e32 v42, v0
	v_mov_b32_e32 v43, v0
	v_mov_b32_e32 v44, v0
	v_mov_b32_e32 v45, v0
	v_mov_b32_e32 v50, v0
	v_mov_b32_e32 v51, v0
	v_mov_b32_e32 v52, v0
	v_mov_b32_e32 v53, v0
	v_mov_b32_e32 v58, v0
	v_mov_b32_e32 v59, v0
	v_mov_b32_e32 v60, v0
	v_mov_b32_e32 v61, v0
	v_mov_b32_e32 v4, v0
	v_mov_b32_e32 v5, v0
	v_mov_b32_e32 v6, v0
	v_mov_b32_e32 v7, v0
	v_mov_b32_e32 v12, v0
	v_mov_b32_e32 v13, v0
	v_mov_b32_e32 v14, v0
	v_mov_b32_e32 v15, v0
	v_mov_b32_e32 v22, v0
	v_mov_b32_e32 v23, v0
	v_mov_b32_e32 v24, v0
	v_mov_b32_e32 v25, v0
	v_mov_b32_e32 v30, v0
	v_mov_b32_e32 v31, v0
	v_mov_b32_e32 v32, v0
	v_mov_b32_e32 v33, v0
	v_mov_b32_e32 v38, v0
	v_mov_b32_e32 v39, v0
	v_mov_b32_e32 v40, v0
	v_mov_b32_e32 v41, v0
	v_mov_b32_e32 v46, v0
	v_mov_b32_e32 v47, v0
	v_mov_b32_e32 v48, v0
	v_mov_b32_e32 v49, v0
	v_mov_b32_e32 v54, v0
	v_mov_b32_e32 v55, v0
	v_mov_b32_e32 v56, v0
	v_mov_b32_e32 v57, v0
	v_mov_b32_e32 v62, v0
	v_mov_b32_e32 v63, v0
	v_mov_b32_e32 v64, v0
	v_mov_b32_e32 v65, v0
	v_mov_b32_e32 v66, v0
	v_mov_b32_e32 v67, v0
	v_mov_b32_e32 v68, v0
	v_mov_b32_e32 v69, v0
	v_mov_b32_e32 v74, v0
	v_mov_b32_e32 v75, v0
	v_mov_b32_e32 v76, v0
	v_mov_b32_e32 v77, v0
	v_mov_b32_e32 v82, v0
	v_mov_b32_e32 v83, v0
	v_mov_b32_e32 v84, v0
	v_mov_b32_e32 v85, v0
	v_mov_b32_e32 v90, v0
	v_mov_b32_e32 v91, v0
	v_mov_b32_e32 v92, v0
	v_mov_b32_e32 v93, v0
	v_mov_b32_e32 v98, v0
	v_mov_b32_e32 v99, v0
	v_mov_b32_e32 v100, v0
	v_mov_b32_e32 v101, v0
	v_mov_b32_e32 v106, v0
	v_mov_b32_e32 v107, v0
	v_mov_b32_e32 v108, v0
	v_mov_b32_e32 v109, v0
	v_mov_b32_e32 v114, v0
	v_mov_b32_e32 v115, v0
	v_mov_b32_e32 v116, v0
	v_mov_b32_e32 v117, v0
	v_mov_b32_e32 v122, v0
	v_mov_b32_e32 v123, v0
	v_mov_b32_e32 v124, v0
	v_mov_b32_e32 v125, v0
	v_mov_b32_e32 v70, v0
	v_mov_b32_e32 v71, v0
	v_mov_b32_e32 v72, v0
	v_mov_b32_e32 v73, v0
	v_mov_b32_e32 v78, v0
	v_mov_b32_e32 v79, v0
	v_mov_b32_e32 v80, v0
	v_mov_b32_e32 v81, v0
	v_mov_b32_e32 v86, v0
	v_mov_b32_e32 v87, v0
	v_mov_b32_e32 v88, v0
	v_mov_b32_e32 v89, v0
	v_mov_b32_e32 v94, v0
	v_mov_b32_e32 v95, v0
	v_mov_b32_e32 v96, v0
	v_mov_b32_e32 v97, v0
	v_mov_b32_e32 v102, v0
	v_mov_b32_e32 v103, v0
	v_mov_b32_e32 v104, v0
	v_mov_b32_e32 v105, v0
	v_mov_b32_e32 v110, v0
	v_mov_b32_e32 v111, v0
	v_mov_b32_e32 v112, v0
	v_mov_b32_e32 v113, v0
	v_mov_b32_e32 v118, v0
	v_mov_b32_e32 v119, v0
	v_mov_b32_e32 v120, v0
	v_mov_b32_e32 v121, v0
	v_mov_b32_e32 v126, v0
	v_mov_b32_e32 v127, v0
	v_mov_b32_e32 v128, v0
	v_mov_b32_e32 v129, v0

.LBB0_2735:
	buffer_wbl2 sc1
	s_waitcnt vmcnt(0)
	s_lshl_b32 s8, s60, 5
	s_add_u32 s8, s6, s8
	s_addc_u32 s9, s7, 0
	s_add_u32 s8, s8, 0x1400
	s_addc_u32 s9, s9, 0
	global_atomic_add v17, v237, s[8:9]
	s_mov_b64 s[12:13], 0
	s_getpc_b64 s[98:99]

	.amdhsa_kernel _Z3fwd4Args
		.amdhsa_group_segment_fixed_size 0
		.amdhsa_private_segment_fixed_size 0
		.amdhsa_kernarg_size 472
		.amdhsa_user_sgpr_count 2
		.amdhsa_user_sgpr_dispatch_ptr 0
		.amdhsa_user_sgpr_queue_ptr 0
		.amdhsa_user_sgpr_kernarg_segment_ptr 1
		.amdhsa_user_sgpr_dispatch_id 0
		.amdhsa_user_sgpr_kernarg_preload_length 0
		.amdhsa_user_sgpr_kernarg_preload_offset 0
		.amdhsa_user_sgpr_private_segment_size 0
		.amdhsa_uses_dynamic_stack 0
		.amdhsa_enable_private_segment 0
		.amdhsa_system_sgpr_workgroup_id_x 1
		.amdhsa_system_sgpr_workgroup_id_y 0
		.amdhsa_system_sgpr_workgroup_id_z 0
		.amdhsa_system_sgpr_workgroup_info 0
		.amdhsa_system_vgpr_workitem_id 0
		.amdhsa_next_free_vgpr 256
		.amdhsa_next_free_sgpr 102
		.amdhsa_accum_offset 256
		.amdhsa_reserve_vcc 1
		.amdhsa_float_round_mode_32 0
		.amdhsa_float_round_mode_16_64 0
		.amdhsa_float_denorm_mode_32 3
		.amdhsa_float_denorm_mode_16_64 3
		.amdhsa_dx10_clamp 1
		.amdhsa_ieee_mode 1
		.amdhsa_fp16_overflow 0
		.amdhsa_tg_split 0
		.amdhsa_exception_fp_ieee_invalid_op 0
		.amdhsa_exception_fp_denorm_src 0
		.amdhsa_exception_fp_ieee_div_zero 0
		.amdhsa_exception_fp_ieee_overflow 0
		.amdhsa_exception_fp_ieee_underflow 0
		.amdhsa_exception_fp_ieee_inexact 0
		.amdhsa_exception_int_div_zero 0
	.end_amdhsa_kernel

amdhsa.kernels:
  - .agpr_count:     0
    .args:
      - .offset:         0
        .size:           216
        .value_kind:     by_value
      - .offset:         216
        .size:           4
        .value_kind:     hidden_block_count_x
      - .offset:         220
        .size:           4
        .value_kind:     hidden_block_count_y
      - .offset:         224
        .size:           4
        .value_kind:     hidden_block_count_z
      - .offset:         228
        .size:           2
        .value_kind:     hidden_group_size_x
      - .offset:         230
        .size:           2
        .value_kind:     hidden_group_size_y
      - .offset:         232
        .size:           2
        .value_kind:     hidden_group_size_z
      - .offset:         234
        .size:           2
        .value_kind:     hidden_remainder_x
      - .offset:         236
        .size:           2
        .value_kind:     hidden_remainder_y
      - .offset:         238
        .size:           2
        .value_kind:     hidden_remainder_z
      - .offset:         256
        .size:           8
        .value_kind:     hidden_global_offset_x
      - .offset:         264
        .size:           8
        .value_kind:     hidden_global_offset_y
      - .offset:         272
        .size:           8
        .value_kind:     hidden_global_offset_z
      - .offset:         280
        .size:           2
        .value_kind:     hidden_grid_dims
      - .offset:         336
        .size:           4
        .value_kind:     hidden_dynamic_lds_size
    .group_segment_fixed_size: 0
    .kernarg_segment_align: 8
    .kernarg_segment_size: 472
    .language:       OpenCL C
    .language_version:
      - 2
      - 0
    .max_flat_workgroup_size: 512
    .name:           _Z3fwd4Args
    .private_segment_fixed_size: 0
    .sgpr_count:     108
    .sgpr_spill_count: 83
    .symbol:         _Z3fwd4Args.kd
    .uniform_work_group_size: 1
    .uses_dynamic_stack: false
    .vgpr_count:     256
    .vgpr_spill_count: 0
    .wavefront_size: 64
